# K-loop heads of both GEMM instances aligned to 64 bytes (.p2align 6 pad before the loop head); on v38
# speedup vs baseline: 1.0303x; 1.0045x over previous
; template <class Epi, class Sched, bool ALIGN_EPI = false, bool SP2 = false>
; __device__ __forceinline__ void gemm_phase(PG8_LAS unsigned char* lds, const Gemm g, const Sched& S, const Epi& E, const int tid) {
;     ...
;         const bool has_next = S.next(ui + 1, nxt);
;         const char* nA = has_next ? (const char*)g.A + (size_t)(nxt.pm >> 3) * g.gsa + (size_t)(nxt.pm & 7) * tstepA : cA; const char* nB = has_next ? (const char*)g.Bt + (size_t)nxt.pn * tstepB : cB;
;     ...
; #pragma unroll
;         for (int a = 0; a < 2; ++a)
; #pragma unroll
;             for (int b = 0; b < 2; ++b)
; #pragma unroll
;                 for (int m = 0; m < 4; ++m)
; #pragma unroll
;                     for (int n = 0; n < 2; ++n) acc[a][b][m][n] = (f32x4){0.f, 0.f, 0.f, 0.f};
;         cur = nxt; cA = nA; cB = nB; ++ui;
.LBB0_34:
	s_ashr_i32 s14, s21, 3
	s_ashr_i32 s15, s14, 31
	v_readlane_b32 s44, v253, 57
	s_lshl_b64 s[14:15], s[14:15], 23
	v_readlane_b32 s58, v254, 7
	v_readlane_b32 s59, v254, 8
	s_add_u32 s13, s58, s14
	s_addc_u32 s15, s59, s15
	s_lshl_b32 s14, s21, 20
	s_and_b32 s14, s14, 0x700000
	s_add_u32 s14, s13, s14
	s_addc_u32 s15, s15, 0
	s_and_b64 s[16:17], s[6:7], exec
	s_cselect_b32 s26, s15, s9
	s_cselect_b32 s27, s14, s8
	s_ashr_i32 s13, s12, 31
	s_lshl_b64 s[16:17], s[12:13], 19
	s_add_u32 s16, s0, s16
	s_addc_u32 s17, s1, s17
	s_and_b64 s[22:23], s[6:7], exec
	s_cselect_b32 s13, s17, s19
	s_cselect_b32 s28, s16, s18
	s_add_u32 s8, s8, 0x80080
	s_addc_u32 s9, s9, 0
	s_add_u32 s29, s18, 0x100
	s_addc_u32 s30, s19, 0
	s_mov_b32 s31, -2
	v_mov_b64_e32 v[0:1], 0
	v_mov_b64_e32 v[2:3], 0
	v_mov_b64_e32 v[4:5], 0
	v_mov_b64_e32 v[6:7], 0
	v_mov_b64_e32 v[8:9], 0
	v_mov_b64_e32 v[10:11], 0
	v_mov_b64_e32 v[12:13], 0
	v_mov_b64_e32 v[14:15], 0
	v_mov_b64_e32 v[16:17], 0
	v_mov_b64_e32 v[18:19], 0
	v_mov_b64_e32 v[20:21], 0
	v_mov_b64_e32 v[22:23], 0
	v_mov_b64_e32 v[24:25], 0
	v_mov_b64_e32 v[26:27], 0
	v_mov_b64_e32 v[28:29], 0
	v_mov_b64_e32 v[30:31], 0
	v_mov_b64_e32 v[32:33], 0
	v_mov_b64_e32 v[34:35], 0
	v_mov_b64_e32 v[36:37], 0
	v_mov_b64_e32 v[38:39], 0
	v_mov_b64_e32 v[40:41], 0
	v_mov_b64_e32 v[42:43], 0
	v_mov_b64_e32 v[44:45], 0
	v_mov_b64_e32 v[46:47], 0
	v_mov_b64_e32 v[48:49], 0
	v_mov_b64_e32 v[50:51], 0
	v_mov_b64_e32 v[52:53], 0
	v_mov_b64_e32 v[54:55], 0
	v_mov_b64_e32 v[56:57], 0
	v_mov_b64_e32 v[58:59], 0
	v_mov_b64_e32 v[60:61], 0
	v_mov_b64_e32 v[62:63], 0
	v_mov_b64_e32 v[64:65], 0
	v_mov_b64_e32 v[66:67], 0
	v_mov_b64_e32 v[68:69], 0
	v_mov_b64_e32 v[70:71], 0
	v_mov_b64_e32 v[72:73], 0
	v_mov_b64_e32 v[74:75], 0
	v_mov_b64_e32 v[76:77], 0
	v_mov_b64_e32 v[78:79], 0
	v_mov_b64_e32 v[80:81], 0
	v_mov_b64_e32 v[82:83], 0
	v_mov_b64_e32 v[84:85], 0
	v_mov_b64_e32 v[86:87], 0
	v_mov_b64_e32 v[88:89], 0
	v_mov_b64_e32 v[90:91], 0
	v_mov_b64_e32 v[92:93], 0
	v_mov_b64_e32 v[94:95], 0
	v_mov_b64_e32 v[96:97], 0
	v_mov_b64_e32 v[98:99], 0
	v_mov_b64_e32 v[100:101], 0
	v_mov_b64_e32 v[102:103], 0
	v_mov_b64_e32 v[104:105], 0
	v_mov_b64_e32 v[106:107], 0
	v_mov_b64_e32 v[108:109], 0
	v_mov_b64_e32 v[110:111], 0
	v_mov_b64_e32 v[112:113], 0
	v_mov_b64_e32 v[114:115], 0
	v_mov_b64_e32 v[116:117], 0
	v_mov_b64_e32 v[118:119], 0
	v_mov_b64_e32 v[120:121], 0
	v_mov_b64_e32 v[122:123], 0
	v_mov_b64_e32 v[124:125], 0
	v_mov_b64_e32 v[126:127], 0
	v_readlane_b32 s45, v253, 58
	v_readlane_b32 s46, v253, 59
	v_readlane_b32 s47, v253, 60
	v_readlane_b32 s48, v253, 61
	v_readlane_b32 s49, v253, 62
	v_readlane_b32 s50, v253, 63
	v_readlane_b32 s51, v254, 0
	v_readlane_b32 s52, v254, 1
	v_readlane_b32 s53, v254, 2
	v_readlane_b32 s54, v254, 3
	v_readlane_b32 s55, v254, 4
	v_readlane_b32 s56, v254, 5
	v_readlane_b32 s57, v254, 6
	.p2align	6

; template <class Epi, class Sched, bool ALIGN_EPI = false, bool SP2 = false>
; __device__ __forceinline__ void gemm_phase(PG8_LAS unsigned char* lds, const Gemm g, const Sched& S, const Epi& E, const int tid) {
;     ...
;         const bool has_next = S.next(ui + 1, nxt);
;         const char* nA = has_next ? (const char*)g.A + (size_t)(nxt.pm >> 3) * g.gsa + (size_t)(nxt.pm & 7) * tstepA : cA; const char* nB = has_next ? (const char*)g.Bt + (size_t)nxt.pn * tstepB : cB;
;     ...
; #pragma unroll
;         for (int a = 0; a < 2; ++a)
; #pragma unroll
;             for (int b = 0; b < 2; ++b)
; #pragma unroll
;                 for (int m = 0; m < 4; ++m)
; #pragma unroll
;                     for (int n = 0; n < 2; ++n) acc[a][b][m][n] = (f32x4){0.f, 0.f, 0.f, 0.f};
;         cur = nxt; cA = nA; cB = nB; ++ui;
.LBB0_467:
	s_ashr_i32 s71, s70, 31
	s_lshl_b64 s[42:43], s[70:71], s97
	s_add_u32 s86, s10, s42
	s_addc_u32 s87, s11, s43
	s_and_b64 s[8:9], s[8:9], exec
	s_cselect_b32 s42, s87, s93
	s_cselect_b32 s43, s86, s92
	s_add_u32 s8, s94, 0x80
	s_addc_u32 s9, s95, 0
	s_add_u32 s44, s92, 0x100
	s_addc_u32 s45, s93, 0
	s_mov_b32 s46, 0
	v_mov_b64_e32 v[0:1], 0
	v_mov_b64_e32 v[2:3], 0
	v_mov_b64_e32 v[4:5], 0
	v_mov_b64_e32 v[6:7], 0
	v_mov_b64_e32 v[8:9], 0
	v_mov_b64_e32 v[10:11], 0
	v_mov_b64_e32 v[12:13], 0
	v_mov_b64_e32 v[14:15], 0
	v_mov_b64_e32 v[16:17], 0
	v_mov_b64_e32 v[18:19], 0
	v_mov_b64_e32 v[20:21], 0
	v_mov_b64_e32 v[22:23], 0
	v_mov_b64_e32 v[24:25], 0
	v_mov_b64_e32 v[26:27], 0
	v_mov_b64_e32 v[28:29], 0
	v_mov_b64_e32 v[30:31], 0
	v_mov_b64_e32 v[32:33], 0
	v_mov_b64_e32 v[34:35], 0
	v_mov_b64_e32 v[36:37], 0
	v_mov_b64_e32 v[38:39], 0
	v_mov_b64_e32 v[40:41], 0
	v_mov_b64_e32 v[42:43], 0
	v_mov_b64_e32 v[44:45], 0
	v_mov_b64_e32 v[46:47], 0
	v_mov_b64_e32 v[48:49], 0
	v_mov_b64_e32 v[50:51], 0
	v_mov_b64_e32 v[52:53], 0
	v_mov_b64_e32 v[54:55], 0
	v_mov_b64_e32 v[56:57], 0
	v_mov_b64_e32 v[58:59], 0
	v_mov_b64_e32 v[60:61], 0
	v_mov_b64_e32 v[62:63], 0
	v_mov_b64_e32 v[64:65], 0
	v_mov_b64_e32 v[66:67], 0
	v_mov_b64_e32 v[68:69], 0
	v_mov_b64_e32 v[70:71], 0
	v_mov_b64_e32 v[72:73], 0
	v_mov_b64_e32 v[74:75], 0
	v_mov_b64_e32 v[76:77], 0
	v_mov_b64_e32 v[78:79], 0
	v_mov_b64_e32 v[80:81], 0
	v_mov_b64_e32 v[82:83], 0
	v_mov_b64_e32 v[84:85], 0
	v_mov_b64_e32 v[86:87], 0
	v_mov_b64_e32 v[88:89], 0
	v_mov_b64_e32 v[90:91], 0
	v_mov_b64_e32 v[92:93], 0
	v_mov_b64_e32 v[94:95], 0
	v_mov_b64_e32 v[96:97], 0
	v_mov_b64_e32 v[98:99], 0
	v_mov_b64_e32 v[100:101], 0
	v_mov_b64_e32 v[102:103], 0
	v_mov_b64_e32 v[104:105], 0
	v_mov_b64_e32 v[106:107], 0
	v_mov_b64_e32 v[108:109], 0
	v_mov_b64_e32 v[110:111], 0
	v_mov_b64_e32 v[112:113], 0
	v_mov_b64_e32 v[114:115], 0
	v_mov_b64_e32 v[116:117], 0
	v_mov_b64_e32 v[118:119], 0
	v_mov_b64_e32 v[120:121], 0
	v_mov_b64_e32 v[122:123], 0
	v_mov_b64_e32 v[124:125], 0
	v_mov_b64_e32 v[126:127], 0
	.p2align	6
